# static priority raise for the LEADING wave half (instead of the trailing half) over each GEMM K-loop; otherwise stack24
# speedup vs baseline: 1.0025x; 1.0009x over previous
; template <class Epi, class Sched, bool ALIGN_EPI = false, bool SP2 = false>
; __device__ __forceinline__ void gemm_phase(PG8_LAS unsigned char* lds, const Gemm g, const Sched& S, const Epi& E) {
;     ...
;         const bool has_next = S.next(ui + 1, nxt);
;         const char* nA = has_next ? (const char*)g.A + (size_t)nxt.pm * tstep : cA; const char* nB = has_next ? (const char*)g.Bt + (size_t)nxt.pn * tstep : cB;
;     ...
;         for (int a = 0; a < 2; ++a)
; #pragma unroll
;             for (int b = 0; b < 2; ++b)
; #pragma unroll
;                 for (int m = 0; m < 4; ++m)
; #pragma unroll
;                     for (int n = 0; n < 2; ++n) acc[a][b][m][n] = (f32x4){0.f, 0.f, 0.f, 0.f};
.LBB0_163:
	s_ashr_i32 s51, s50, 31
	s_lshl_b64 s[36:37], s[50:51], 19
	s_add_u32 s62, s2, s36
	s_addc_u32 s63, s14, s37
	s_and_b64 s[36:37], s[40:41], exec
	s_cselect_b32 s36, s63, s65
	s_cselect_b32 s37, s62, s64
	s_ashr_i32 s53, s52, 31
	s_lshl_b64 s[66:67], s[52:53], 19
	s_add_u32 s66, s15, s66
	s_addc_u32 s67, s16, s67
	s_and_b64 s[72:73], s[40:41], exec
	s_cselect_b32 s51, s67, s59
	s_cselect_b32 s53, s66, s58
	s_add_u32 s72, s64, 0x40080
	s_addc_u32 s73, s65, 0
	s_add_u32 s92, s58, 0x100
	v_mov_b64_e32 v[0:1], 0
	s_addc_u32 s93, s59, 0
	s_mov_b32 s94, -2
	v_mov_b64_e32 v[2:3], 0
	v_mov_b64_e32 v[4:5], 0
	v_mov_b64_e32 v[6:7], 0
	v_mov_b64_e32 v[8:9], 0
	v_mov_b64_e32 v[10:11], 0
	v_mov_b64_e32 v[12:13], 0
	v_mov_b64_e32 v[14:15], 0
	v_mov_b64_e32 v[16:17], 0
	v_mov_b64_e32 v[18:19], 0
	v_mov_b64_e32 v[20:21], 0
	v_mov_b64_e32 v[22:23], 0
	v_mov_b64_e32 v[24:25], 0
	v_mov_b64_e32 v[26:27], 0
	v_mov_b64_e32 v[28:29], 0
	v_mov_b64_e32 v[30:31], 0
	v_mov_b64_e32 v[32:33], 0
	v_mov_b64_e32 v[34:35], 0
	v_mov_b64_e32 v[36:37], 0
	v_mov_b64_e32 v[38:39], 0
	v_mov_b64_e32 v[40:41], 0
	v_mov_b64_e32 v[42:43], 0
	v_mov_b64_e32 v[44:45], 0
	v_mov_b64_e32 v[46:47], 0
	v_mov_b64_e32 v[48:49], 0
	v_mov_b64_e32 v[50:51], 0
	v_mov_b64_e32 v[52:53], 0
	v_mov_b64_e32 v[54:55], 0
	v_mov_b64_e32 v[56:57], 0
	v_mov_b64_e32 v[58:59], 0
	v_mov_b64_e32 v[60:61], 0
	v_mov_b64_e32 v[62:63], 0
	v_mov_b64_e32 v[64:65], 0
	v_mov_b64_e32 v[66:67], 0
	v_mov_b64_e32 v[68:69], 0
	v_mov_b64_e32 v[70:71], 0
	v_mov_b64_e32 v[72:73], 0
	v_mov_b64_e32 v[74:75], 0
	v_mov_b64_e32 v[76:77], 0
	v_mov_b64_e32 v[78:79], 0
	v_mov_b64_e32 v[80:81], 0
	v_mov_b64_e32 v[82:83], 0
	v_mov_b64_e32 v[84:85], 0
	v_mov_b64_e32 v[86:87], 0
	v_mov_b64_e32 v[88:89], 0
	v_mov_b64_e32 v[90:91], 0
	v_mov_b64_e32 v[92:93], 0
	v_mov_b64_e32 v[94:95], 0
	v_mov_b64_e32 v[96:97], 0
	v_mov_b64_e32 v[98:99], 0
	v_mov_b64_e32 v[100:101], 0
	v_mov_b64_e32 v[102:103], 0
	v_mov_b64_e32 v[104:105], 0
	v_mov_b64_e32 v[106:107], 0
	v_mov_b64_e32 v[108:109], 0
	v_mov_b64_e32 v[110:111], 0
	v_mov_b64_e32 v[112:113], 0
	v_mov_b64_e32 v[114:115], 0
	v_mov_b64_e32 v[116:117], 0
	v_mov_b64_e32 v[118:119], 0
	v_mov_b64_e32 v[120:121], 0
	v_mov_b64_e32 v[122:123], 0
	v_mov_b64_e32 v[124:125], 0
	v_mov_b64_e32 v[126:127], 0
	s_and_b64 s[98:99], exec, s[48:49]
	s_cbranch_scc0 .Lsp_1
	s_setprio 1

; template <class Epi, class Sched, bool ALIGN_EPI = false, bool SP2 = false>
; __device__ __forceinline__ void gemm_phase(PG8_LAS unsigned char* lds, const Gemm g, const Sched& S, const Epi& E) {
;     ...
;         const bool has_next = S.next(ui + 1, nxt);
;         const char* nA = has_next ? (const char*)g.A + (size_t)nxt.pm * tstep : cA; const char* nB = has_next ? (const char*)g.Bt + (size_t)nxt.pn * tstep : cB;
;     ...
;         for (int a = 0; a < 2; ++a)
; #pragma unroll
;             for (int b = 0; b < 2; ++b)
; #pragma unroll
;                 for (int m = 0; m < 4; ++m)
; #pragma unroll
;                     for (int n = 0; n < 2; ++n) acc[a][b][m][n] = (f32x4){0.f, 0.f, 0.f, 0.f};
.LBB0_563:
	s_ashr_i32 s67, s66, 31
	s_lshl_b64 s[36:37], s[66:67], 19
	s_add_u32 s64, s2, s36
	s_addc_u32 s65, s25, s37
	s_and_b64 s[36:37], s[40:41], exec
	s_cselect_b32 s36, s65, s93
	s_cselect_b32 s37, s64, s92
	s_ashr_i32 s73, s72, 31
	s_lshl_b64 s[84:85], s[72:73], 19
	s_add_u32 s96, s70, s84
	s_addc_u32 s97, s16, s85
	s_and_b64 s[84:85], s[40:41], exec
	s_cselect_b32 s67, s97, s59
	s_cselect_b32 s73, s96, s58
	s_add_u32 vcc_lo, s92, 0x40080
	s_addc_u32 vcc_hi, s93, 0
	s_add_u32 s88, s58, 0x100
	v_mov_b64_e32 v[0:1], 0
	s_addc_u32 s94, s59, 0
	s_mov_b32 s84, -2
	v_mov_b64_e32 v[2:3], 0
	v_mov_b64_e32 v[4:5], 0
	v_mov_b64_e32 v[6:7], 0
	v_mov_b64_e32 v[16:17], 0
	v_mov_b64_e32 v[18:19], 0
	v_mov_b64_e32 v[20:21], 0
	v_mov_b64_e32 v[22:23], 0
	v_mov_b64_e32 v[32:33], 0
	v_mov_b64_e32 v[34:35], 0
	v_mov_b64_e32 v[36:37], 0
	v_mov_b64_e32 v[38:39], 0
	v_mov_b64_e32 v[48:49], 0
	v_mov_b64_e32 v[50:51], 0
	v_mov_b64_e32 v[52:53], 0
	v_mov_b64_e32 v[54:55], 0
	v_mov_b64_e32 v[8:9], 0
	v_mov_b64_e32 v[10:11], 0
	v_mov_b64_e32 v[12:13], 0
	v_mov_b64_e32 v[14:15], 0
	v_mov_b64_e32 v[24:25], 0
	v_mov_b64_e32 v[26:27], 0
	v_mov_b64_e32 v[28:29], 0
	v_mov_b64_e32 v[30:31], 0
	v_mov_b64_e32 v[40:41], 0
	v_mov_b64_e32 v[42:43], 0
	v_mov_b64_e32 v[44:45], 0
	v_mov_b64_e32 v[46:47], 0
	v_mov_b64_e32 v[56:57], 0
	v_mov_b64_e32 v[58:59], 0
	v_mov_b64_e32 v[60:61], 0
	v_mov_b64_e32 v[62:63], 0
	v_mov_b64_e32 v[64:65], 0
	v_mov_b64_e32 v[66:67], 0
	v_mov_b64_e32 v[68:69], 0
	v_mov_b64_e32 v[70:71], 0
	v_mov_b64_e32 v[80:81], 0
	v_mov_b64_e32 v[82:83], 0
	v_mov_b64_e32 v[84:85], 0
	v_mov_b64_e32 v[86:87], 0
	v_mov_b64_e32 v[96:97], 0
	v_mov_b64_e32 v[98:99], 0
	v_mov_b64_e32 v[100:101], 0
	v_mov_b64_e32 v[102:103], 0
	v_mov_b64_e32 v[112:113], 0
	v_mov_b64_e32 v[114:115], 0
	v_mov_b64_e32 v[116:117], 0
	v_mov_b64_e32 v[118:119], 0
	v_mov_b64_e32 v[72:73], 0
	v_mov_b64_e32 v[74:75], 0
	v_mov_b64_e32 v[76:77], 0
	v_mov_b64_e32 v[78:79], 0
	v_mov_b64_e32 v[88:89], 0
	v_mov_b64_e32 v[90:91], 0
	v_mov_b64_e32 v[92:93], 0
	v_mov_b64_e32 v[94:95], 0
	v_mov_b64_e32 v[104:105], 0
	v_mov_b64_e32 v[106:107], 0
	v_mov_b64_e32 v[108:109], 0
	v_mov_b64_e32 v[110:111], 0
	v_mov_b64_e32 v[120:121], 0
	v_mov_b64_e32 v[122:123], 0
	v_mov_b64_e32 v[124:125], 0
	v_mov_b64_e32 v[126:127], 0
	s_and_b64 s[98:99], exec, s[62:63]
	s_cbranch_scc0 .Lsp_2
	s_setprio 1

; template <class Epi, class Sched, bool ALIGN_EPI = false, bool SP2 = false>
; __device__ __forceinline__ void gemm_phase(PG8_LAS unsigned char* lds, const Gemm g, const Sched& S, const Epi& E) {
;     ...
;         const bool has_next = S.next(ui + 1, nxt);
;         const char* nA = has_next ? (const char*)g.A + (size_t)nxt.pm * tstep : cA; const char* nB = has_next ? (const char*)g.Bt + (size_t)nxt.pn * tstep : cB;
;     ...
;         for (int a = 0; a < 2; ++a)
; #pragma unroll
;             for (int b = 0; b < 2; ++b)
; #pragma unroll
;                 for (int m = 0; m < 4; ++m)
; #pragma unroll
;                     for (int n = 0; n < 2; ++n) acc[a][b][m][n] = (f32x4){0.f, 0.f, 0.f, 0.f};
.LBB0_597:
	s_ashr_i32 s93, s92, 31
	s_lshl_b64 s[36:37], s[92:93], 19
	s_add_u32 s44, s2, s36
	s_addc_u32 s45, s25, s37
	s_and_b64 s[36:37], s[40:41], exec
	s_cselect_b32 s35, s45, s65
	s_cselect_b32 s36, s44, s64
	s_ashr_i32 s97, s96, 31
	s_lshl_b64 s[62:63], s[96:97], 19
	s_add_u32 s62, s70, s62
	s_addc_u32 s63, s16, s63
	s_and_b64 s[84:85], s[40:41], exec
	s_cselect_b32 s37, s63, s59
	s_cselect_b32 s43, s62, s58
	s_add_u32 vcc_lo, s64, 0x40080
	s_addc_u32 vcc_hi, s65, 0
	s_add_u32 s88, s58, 0x100
	v_mov_b64_e32 v[0:1], 0
	s_addc_u32 s93, s59, 0
	s_mov_b32 s94, -2
	v_mov_b64_e32 v[2:3], 0
	v_mov_b64_e32 v[4:5], 0
	v_mov_b64_e32 v[6:7], 0
	v_mov_b64_e32 v[16:17], 0
	v_mov_b64_e32 v[18:19], 0
	v_mov_b64_e32 v[20:21], 0
	v_mov_b64_e32 v[22:23], 0
	v_mov_b64_e32 v[32:33], 0
	v_mov_b64_e32 v[34:35], 0
	v_mov_b64_e32 v[36:37], 0
	v_mov_b64_e32 v[38:39], 0
	v_mov_b64_e32 v[40:41], 0
	v_mov_b64_e32 v[42:43], 0
	v_mov_b64_e32 v[48:49], 0
	v_mov_b64_e32 v[50:51], 0
	v_mov_b64_e32 v[8:9], 0
	v_mov_b64_e32 v[10:11], 0
	v_mov_b64_e32 v[12:13], 0
	v_mov_b64_e32 v[14:15], 0
	v_mov_b64_e32 v[24:25], 0
	v_mov_b64_e32 v[26:27], 0
	v_mov_b64_e32 v[28:29], 0
	v_mov_b64_e32 v[30:31], 0
	v_mov_b64_e32 v[44:45], 0
	v_mov_b64_e32 v[46:47], 0
	v_mov_b64_e32 v[52:53], 0
	v_mov_b64_e32 v[54:55], 0
	v_mov_b64_e32 v[56:57], 0
	v_mov_b64_e32 v[58:59], 0
	v_mov_b64_e32 v[60:61], 0
	v_mov_b64_e32 v[62:63], 0
	v_mov_b64_e32 v[80:81], 0
	v_mov_b64_e32 v[82:83], 0
	v_mov_b64_e32 v[84:85], 0
	v_mov_b64_e32 v[86:87], 0
	v_mov_b64_e32 v[88:89], 0
	v_mov_b64_e32 v[90:91], 0
	v_mov_b64_e32 v[96:97], 0
	v_mov_b64_e32 v[98:99], 0
	v_mov_b64_e32 v[112:113], 0
	v_mov_b64_e32 v[114:115], 0
	v_mov_b64_e32 v[116:117], 0
	v_mov_b64_e32 v[118:119], 0
	v_mov_b64_e32 v[120:121], 0
	v_mov_b64_e32 v[122:123], 0
	v_mov_b64_e32 v[130:131], 0
	v_mov_b64_e32 v[132:133], 0
	v_mov_b64_e32 v[92:93], 0
	v_mov_b64_e32 v[94:95], 0
	v_mov_b64_e32 v[100:101], 0
	v_mov_b64_e32 v[102:103], 0
	v_mov_b64_e32 v[104:105], 0
	v_mov_b64_e32 v[106:107], 0
	v_mov_b64_e32 v[108:109], 0
	v_mov_b64_e32 v[110:111], 0
	v_mov_b64_e32 v[124:125], 0
	v_mov_b64_e32 v[126:127], 0
	v_mov_b64_e32 v[134:135], 0
	v_mov_b64_e32 v[136:137], 0
	v_mov_b64_e32 v[138:139], 0
	v_mov_b64_e32 v[140:141], 0
	v_mov_b64_e32 v[142:143], 0
	v_mov_b64_e32 v[144:145], 0
	s_and_b64 s[98:99], exec, s[72:73]
	s_cbranch_scc0 .Lsp_3
	s_setprio 1

; template <class Epi, class Sched, bool ALIGN_EPI = false, bool SP2 = false>
; __device__ __forceinline__ void gemm_phase(PG8_LAS unsigned char* lds, const Gemm g, const Sched& S, const Epi& E) {
;     ...
;         const bool has_next = S.next(ui + 1, nxt);
;         const char* nA = has_next ? (const char*)g.A + (size_t)nxt.pm * tstep : cA; const char* nB = has_next ? (const char*)g.Bt + (size_t)nxt.pn * tstep : cB;
;     ...
;         for (int a = 0; a < 2; ++a)
; #pragma unroll
;             for (int b = 0; b < 2; ++b)
; #pragma unroll
;                 for (int m = 0; m < 4; ++m)
; #pragma unroll
;                     for (int n = 0; n < 2; ++n) acc[a][b][m][n] = (f32x4){0.f, 0.f, 0.f, 0.f};
.LBB0_812:
	s_ashr_i32 s49, s48, 31
	s_lshl_b64 s[28:29], s[48:49], 19
	s_add_u32 s52, s2, s28
	s_addc_u32 s53, s14, s29
	s_and_b64 s[28:29], s[38:39], exec
	s_cselect_b32 s28, s53, s65
	s_cselect_b32 s29, s52, s64
	s_ashr_i32 s51, s50, 31
	s_lshl_b64 s[30:31], s[50:51], 19
	s_add_u32 s62, s15, s30
	s_addc_u32 s63, s16, s31
	s_and_b64 s[30:31], s[38:39], exec
	s_cselect_b32 s30, s63, s59
	s_cselect_b32 s31, s62, s58
	s_add_u32 s66, s64, 0x40080
	s_addc_u32 s67, s65, 0
	s_add_u32 s34, s58, 0x100
	v_mov_b64_e32 v[0:1], 0
	s_addc_u32 s35, s59, 0
	s_mov_b32 s36, -2
	v_mov_b64_e32 v[2:3], 0
	v_mov_b64_e32 v[8:9], 0
	v_mov_b64_e32 v[10:11], 0
	v_mov_b64_e32 v[16:17], 0
	v_mov_b64_e32 v[18:19], 0
	v_mov_b64_e32 v[24:25], 0
	v_mov_b64_e32 v[26:27], 0
	v_mov_b64_e32 v[32:33], 0
	v_mov_b64_e32 v[34:35], 0
	v_mov_b64_e32 v[40:41], 0
	v_mov_b64_e32 v[42:43], 0
	v_mov_b64_e32 v[48:49], 0
	v_mov_b64_e32 v[50:51], 0
	v_mov_b64_e32 v[56:57], 0
	v_mov_b64_e32 v[58:59], 0
	v_mov_b64_e32 v[4:5], 0
	v_mov_b64_e32 v[6:7], 0
	v_mov_b64_e32 v[12:13], 0
	v_mov_b64_e32 v[14:15], 0
	v_mov_b64_e32 v[20:21], 0
	v_mov_b64_e32 v[22:23], 0
	v_mov_b64_e32 v[28:29], 0
	v_mov_b64_e32 v[30:31], 0
	v_mov_b64_e32 v[36:37], 0
	v_mov_b64_e32 v[38:39], 0
	v_mov_b64_e32 v[44:45], 0
	v_mov_b64_e32 v[46:47], 0
	v_mov_b64_e32 v[52:53], 0
	v_mov_b64_e32 v[54:55], 0
	v_mov_b64_e32 v[60:61], 0
	v_mov_b64_e32 v[62:63], 0
	v_mov_b64_e32 v[64:65], 0
	v_mov_b64_e32 v[66:67], 0
	v_mov_b64_e32 v[72:73], 0
	v_mov_b64_e32 v[74:75], 0
	v_mov_b64_e32 v[80:81], 0
	v_mov_b64_e32 v[82:83], 0
	v_mov_b64_e32 v[88:89], 0
	v_mov_b64_e32 v[90:91], 0
	v_mov_b64_e32 v[96:97], 0
	v_mov_b64_e32 v[98:99], 0
	v_mov_b64_e32 v[104:105], 0
	v_mov_b64_e32 v[106:107], 0
	v_mov_b64_e32 v[112:113], 0
	v_mov_b64_e32 v[114:115], 0
	v_mov_b64_e32 v[120:121], 0
	v_mov_b64_e32 v[122:123], 0
	v_mov_b64_e32 v[68:69], 0
	v_mov_b64_e32 v[70:71], 0
	v_mov_b64_e32 v[76:77], 0
	v_mov_b64_e32 v[78:79], 0
	v_mov_b64_e32 v[84:85], 0
	v_mov_b64_e32 v[86:87], 0
	v_mov_b64_e32 v[92:93], 0
	v_mov_b64_e32 v[94:95], 0
	v_mov_b64_e32 v[100:101], 0
	v_mov_b64_e32 v[102:103], 0
	v_mov_b64_e32 v[108:109], 0
	v_mov_b64_e32 v[110:111], 0
	v_mov_b64_e32 v[116:117], 0
	v_mov_b64_e32 v[118:119], 0
	v_mov_b64_e32 v[124:125], 0
	v_mov_b64_e32 v[126:127], 0
	s_and_b64 s[98:99], exec, s[46:47]
	s_cbranch_scc0 .Lsp_0
	s_setprio 1

; template <class Epi, class Sched, bool ALIGN_EPI = false, bool SP2 = false>
; __device__ __forceinline__ void gemm_phase(PG8_LAS unsigned char* lds, const Gemm g, const Sched& S, const Epi& E) {
;     ...
;             const char* a2 = last ? nA : cA + (size_t)(t + 2) * kstep; const char* b2 = last ? nB : cB + (size_t)(t + 2) * kstep;
;     ...
;         for (int a = 0; a < 2; ++a)
; #pragma unroll
;             for (int b = 0; b < 2; ++b)
; #pragma unroll
;                 for (int m = 0; m < 4; ++m)
; #pragma unroll
;                     for (int n = 0; n < 2; ++n) acc[a][b][m][n] = (f32x4){0.f, 0.f, 0.f, 0.f};
.LBB0_956:
	s_add_u32 s36, s46, 0x100
	v_mov_b64_e32 v[0:1], 0
	s_addc_u32 s37, s47, 0
	s_mov_b32 s70, -2
	v_mov_b64_e32 v[2:3], 0
	v_mov_b64_e32 v[4:5], 0
	v_mov_b64_e32 v[6:7], 0
	v_mov_b64_e32 v[16:17], 0
	v_mov_b64_e32 v[18:19], 0
	v_mov_b64_e32 v[20:21], 0
	v_mov_b64_e32 v[22:23], 0
	v_mov_b64_e32 v[32:33], 0
	v_mov_b64_e32 v[34:35], 0
	v_mov_b64_e32 v[36:37], 0
	v_mov_b64_e32 v[38:39], 0
	v_mov_b64_e32 v[48:49], 0
	v_mov_b64_e32 v[50:51], 0
	v_mov_b64_e32 v[52:53], 0
	v_mov_b64_e32 v[54:55], 0
	v_mov_b64_e32 v[8:9], 0
	v_mov_b64_e32 v[10:11], 0
	v_mov_b64_e32 v[12:13], 0
	v_mov_b64_e32 v[14:15], 0
	v_mov_b64_e32 v[24:25], 0
	v_mov_b64_e32 v[26:27], 0
	v_mov_b64_e32 v[28:29], 0
	v_mov_b64_e32 v[30:31], 0
	v_mov_b64_e32 v[40:41], 0
	v_mov_b64_e32 v[42:43], 0
	v_mov_b64_e32 v[44:45], 0
	v_mov_b64_e32 v[46:47], 0
	v_mov_b64_e32 v[56:57], 0
	v_mov_b64_e32 v[58:59], 0
	v_mov_b64_e32 v[60:61], 0
	v_mov_b64_e32 v[62:63], 0
	v_mov_b64_e32 v[64:65], 0
	v_mov_b64_e32 v[66:67], 0
	v_mov_b64_e32 v[68:69], 0
	v_mov_b64_e32 v[70:71], 0
	v_mov_b64_e32 v[80:81], 0
	v_mov_b64_e32 v[82:83], 0
	v_mov_b64_e32 v[84:85], 0
	v_mov_b64_e32 v[86:87], 0
	v_mov_b64_e32 v[96:97], 0
	v_mov_b64_e32 v[98:99], 0
	v_mov_b64_e32 v[100:101], 0
	v_mov_b64_e32 v[102:103], 0
	v_mov_b64_e32 v[112:113], 0
	v_mov_b64_e32 v[114:115], 0
	v_mov_b64_e32 v[116:117], 0
	v_mov_b64_e32 v[118:119], 0
	v_mov_b64_e32 v[72:73], 0
	v_mov_b64_e32 v[74:75], 0
	v_mov_b64_e32 v[76:77], 0
	v_mov_b64_e32 v[78:79], 0
	v_mov_b64_e32 v[88:89], 0
	v_mov_b64_e32 v[90:91], 0
	v_mov_b64_e32 v[92:93], 0
	v_mov_b64_e32 v[94:95], 0
	v_mov_b64_e32 v[104:105], 0
	v_mov_b64_e32 v[106:107], 0
	v_mov_b64_e32 v[108:109], 0
	v_mov_b64_e32 v[110:111], 0
	v_mov_b64_e32 v[120:121], 0
	v_mov_b64_e32 v[122:123], 0
	v_mov_b64_e32 v[124:125], 0
	v_mov_b64_e32 v[126:127], 0
	s_and_b64 s[98:99], exec, s[58:59]
	s_cbranch_scc0 .Lsp_4
	s_setprio 1

; template <class Epi, class Sched, bool ALIGN_EPI = false, bool SP2 = false>
; __device__ __forceinline__ void gemm_phase(PG8_LAS unsigned char* lds, const Gemm g, const Sched& S, const Epi& E) {
;     ...
;             const char* a2 = last ? nA : cA + (size_t)(t + 2) * kstep; const char* b2 = last ? nB : cB + (size_t)(t + 2) * kstep;
;     ...
;         for (int a = 0; a < 2; ++a)
; #pragma unroll
;             for (int b = 0; b < 2; ++b)
; #pragma unroll
;                 for (int m = 0; m < 4; ++m)
; #pragma unroll
;                     for (int n = 0; n < 2; ++n) acc[a][b][m][n] = (f32x4){0.f, 0.f, 0.f, 0.f};
.LBB0_994:
	s_add_u32 s36, s46, 0x100
	v_mov_b64_e32 v[0:1], 0
	s_addc_u32 s37, s47, 0
	s_mov_b32 s84, -2
	v_mov_b64_e32 v[2:3], 0
	v_mov_b64_e32 v[4:5], 0
	v_mov_b64_e32 v[6:7], 0
	v_mov_b64_e32 v[16:17], 0
	v_mov_b64_e32 v[18:19], 0
	v_mov_b64_e32 v[20:21], 0
	v_mov_b64_e32 v[22:23], 0
	v_mov_b64_e32 v[32:33], 0
	v_mov_b64_e32 v[34:35], 0
	v_mov_b64_e32 v[36:37], 0
	v_mov_b64_e32 v[38:39], 0
	v_mov_b64_e32 v[48:49], 0
	v_mov_b64_e32 v[50:51], 0
	v_mov_b64_e32 v[52:53], 0
	v_mov_b64_e32 v[54:55], 0
	v_mov_b64_e32 v[8:9], 0
	v_mov_b64_e32 v[10:11], 0
	v_mov_b64_e32 v[12:13], 0
	v_mov_b64_e32 v[14:15], 0
	v_mov_b64_e32 v[24:25], 0
	v_mov_b64_e32 v[26:27], 0
	v_mov_b64_e32 v[28:29], 0
	v_mov_b64_e32 v[30:31], 0
	v_mov_b64_e32 v[40:41], 0
	v_mov_b64_e32 v[42:43], 0
	v_mov_b64_e32 v[44:45], 0
	v_mov_b64_e32 v[46:47], 0
	v_mov_b64_e32 v[56:57], 0
	v_mov_b64_e32 v[58:59], 0
	v_mov_b64_e32 v[60:61], 0
	v_mov_b64_e32 v[62:63], 0
	v_mov_b64_e32 v[64:65], 0
	v_mov_b64_e32 v[66:67], 0
	v_mov_b64_e32 v[68:69], 0
	v_mov_b64_e32 v[70:71], 0
	v_mov_b64_e32 v[80:81], 0
	v_mov_b64_e32 v[82:83], 0
	v_mov_b64_e32 v[84:85], 0
	v_mov_b64_e32 v[86:87], 0
	v_mov_b64_e32 v[96:97], 0
	v_mov_b64_e32 v[98:99], 0
	v_mov_b64_e32 v[100:101], 0
	v_mov_b64_e32 v[102:103], 0
	v_mov_b64_e32 v[112:113], 0
	v_mov_b64_e32 v[114:115], 0
	v_mov_b64_e32 v[116:117], 0
	v_mov_b64_e32 v[118:119], 0
	v_mov_b64_e32 v[72:73], 0
	v_mov_b64_e32 v[74:75], 0
	v_mov_b64_e32 v[76:77], 0
	v_mov_b64_e32 v[78:79], 0
	v_mov_b64_e32 v[88:89], 0
	v_mov_b64_e32 v[90:91], 0
	v_mov_b64_e32 v[92:93], 0
	v_mov_b64_e32 v[94:95], 0
	v_mov_b64_e32 v[104:105], 0
	v_mov_b64_e32 v[106:107], 0
	v_mov_b64_e32 v[108:109], 0
	v_mov_b64_e32 v[110:111], 0
	v_mov_b64_e32 v[120:121], 0
	v_mov_b64_e32 v[122:123], 0
	v_mov_b64_e32 v[124:125], 0
	v_mov_b64_e32 v[126:127], 0
	s_and_b64 s[98:99], exec, s[62:63]
	s_cbranch_scc0 .Lsp_5
	s_setprio 1
